# LRU tile loop: z (silu(za)) bf16 loaded with d16_hi into zero-low registers, 16 more shifts per tile removed (on top of the sigmoid-fma / clamp trim)
# baseline (speedup 1.0000x reference)
; #define GAS __attribute__((address_space(1)))
; #define LAS __attribute__((address_space(3)))
; __device__ __forceinline__ v4u pack8(const float* v) { v4u w; w.x = pk2(v[0], v[1]); w.y = pk2(v[2], v[3]); w.z = pk2(v[4], v[5]); w.w = pk2(v[6], v[7]); return w; }
; __device__ __forceinline__ void lru_unit(Frame& F, int seq, int n) {
;     ...
;     const int dl = 16 * w + (lane & 15), tq = lane >> 4, dg = 128 * n + dl;
;     const float brg = F.in[11][dg], big = F.in[13][dg];
;     float nsp; { const float x = -F.in[14][dg]; const float sp = fmaxf(x, 0.f) + log1pf(expf(-fabsf(x))); nsp = -8.f * LOG2E * sp; }
;     bf16x8 Br[4], Bi[4];
;     { const bf16* WG = (const bf16*)(F.ws + WS_WG) + (size_t)(2 * n) * 16384;
; #pragma unroll
;       for (int kk = 0; kk < 4; ++kk) { Br[kk] = *(const GAS bf16x8*)(WG + (size_t)dl * 128 + 32 * kk + 8 * tq); Bi[kk] = *(const GAS bf16x8*)(WG + 16384 + (size_t)dl * 128 + 32 * kk + 8 * tq); } }
;     float hc = smp ? F.in[5][b * DM + dg] : 0.f;
;     if (tid < 48) { const int hr = tid >> 4; float x[8];
;         if (smp) { const GAS f32x4* sp_ = (const GAS f32x4*)(F.in[4] + (size_t)(b * 3 + hr) * DM + c0); const f32x4 s0 = sp_[0], s1 = sp_[1];
;             x[0] = s0.x; x[1] = s0.y; x[2] = s0.z; x[3] = s0.w; x[4] = s1.x; x[5] = s1.y; x[6] = s1.z; x[7] = s1.w; }
;         else {
; #pragma unroll
;             for (int e = 0; e < 8; ++e) x[e] = 0.f; }
;         *(LAS v4u*)(HALO + hr * 136 + 8 * cg) = pack8(x); }
;     v4u xr0, xr1; unsigned short zc[16], zn[16];
;     const bf16* xsrc = XA + (rowbase + ct) * DM + c0; const bf16* zsrc = ZA + (rowbase + 4 * tq) * DM + dg;
;     xr0 = *(const GAS v4u*)(xsrc); xr1 = *(const GAS v4u*)(xsrc + (size_t)32 * DM);
; #pragma unroll
;     for (int i = 0; i < 16; ++i) zc[i] = *(const GAS unsigned short*)(zsrc + (size_t)(16 * (i >> 2) + (i & 3)) * DM);
.LBB0_437:
	s_or_b64 exec, exec, s[4:5]
	s_waitcnt vmcnt(8)
	s_mov_b32 s90, 0xbfb8aa3b
	v_mul_f32_e32 v143, 0xbfb8aa3b, v143
	v_mul_f32_e32 v144, 0xbfb8aa3b, v144
	v_mul_f32_e64 v74, |v85|, s15
	v_rndne_f32_e32 v75, v74
	v_sub_f32_e32 v76, v74, v75
	v_fma_f32 v74, |v85|, s15, -v74
	s_mov_b32 s0, 0xb2a5705f
	v_fma_f32 v74, |v85|, s0, v74
	v_add_f32_e32 v74, v76, v74
	v_exp_f32_e32 v74, v74
	v_cvt_i32_f32_e32 v75, v75
	s_mov_b32 s0, 0x42ce8ed0
	v_cmp_ngt_f32_e64 vcc, |v85|, s0
	v_max_f32_e64 v76, -v85, -v85
	v_ldexp_f32 v74, v74, v75
	v_cndmask_b32_e32 v74, 0, v74, vcc
	v_cmp_nlt_f32_e64 vcc, |v85|, s34
	v_max_f32_e32 v100, 0, v76
	s_movk_i32 s0, 0x1000
	v_cndmask_b32_e32 v101, v127, v74, vcc
	v_add_f32_e32 v76, 1.0, v101
	v_add_f32_e32 v74, -1.0, v76
	v_sub_f32_e32 v75, v74, v76
	v_add_f32_e32 v75, 1.0, v75
	v_sub_f32_e32 v74, v101, v74
	v_add_f32_e32 v77, v74, v75
	v_frexp_mant_f32_e32 v78, v76
	v_cvt_f64_f32_e32 v[74:75], v76
	v_frexp_exp_i32_f64_e32 v74, v[74:75]
	v_cmp_gt_f32_e32 vcc, s50, v78
	v_add_u32_e32 v151, 0x2200, v83
	v_cmp_eq_u32_e64 s[4:5], 0, v91
	v_subbrev_co_u32_e32 v74, vcc, 0, v74, vcc
	v_sub_u32_e32 v75, 0, v74
	v_ldexp_f32 v76, v76, v75
	v_ldexp_f32 v75, v77, v75
	v_add_f32_e32 v77, -1.0, v76
	v_add_f32_e32 v80, 1.0, v76
	v_add_f32_e32 v78, 1.0, v77
	v_add_f32_e32 v81, -1.0, v80
	v_sub_f32_e32 v78, v76, v78
	v_sub_f32_e32 v76, v76, v81
	v_add_f32_e32 v78, v75, v78
	v_add_f32_e32 v75, v75, v76
	v_add_f32_e32 v76, v80, v75
	v_rcp_f32_e32 v81, v76
	v_add_f32_e32 v79, v77, v78
	v_sub_f32_e32 v77, v77, v79
	v_add_f32_e32 v77, v78, v77
	v_sub_f32_e32 v78, v80, v76
	v_add_f32_e32 v75, v75, v78
	v_mul_f32_e32 v78, v79, v81
	v_mul_f32_e32 v80, v76, v78
	v_fma_f32 v85, v78, v76, -v80
	v_fmac_f32_e32 v85, v78, v75
	v_add_f32_e32 v86, v80, v85
	v_sub_f32_e32 v87, v79, v86
	v_sub_f32_e32 v79, v79, v87
	v_sub_f32_e32 v80, v86, v80
	v_sub_f32_e32 v79, v79, v86
	v_add_f32_e32 v77, v77, v79
	v_sub_f32_e32 v79, v80, v85
	v_add_f32_e32 v77, v79, v77
	v_add_f32_e32 v79, v87, v77
	v_mul_f32_e32 v80, v81, v79
	v_mul_f32_e32 v85, v76, v80
	v_fma_f32 v76, v80, v76, -v85
	v_fmac_f32_e32 v76, v80, v75
	v_sub_f32_e32 v75, v87, v79
	v_add_f32_e32 v75, v77, v75
	v_add_f32_e32 v77, v85, v76
	v_sub_f32_e32 v86, v79, v77
	v_sub_f32_e32 v79, v79, v86
	v_sub_f32_e32 v85, v77, v85
	v_sub_f32_e32 v77, v79, v77
	v_add_f32_e32 v75, v75, v77
	v_sub_f32_e32 v76, v85, v76
	v_cvt_f32_i32_e32 v74, v74
	v_add_f32_e32 v75, v76, v75
	v_add_f32_e32 v76, v78, v80
	v_add_f32_e32 v75, v86, v75
	v_sub_f32_e32 v77, v76, v78
	v_mul_f32_e32 v75, v81, v75
	v_sub_f32_e32 v77, v80, v77
	v_add_f32_e32 v75, v77, v75
	v_mul_f32_e32 v80, 0x3f317218, v74
	v_add_f32_e32 v77, v76, v75
	v_fma_f32 v81, v74, s51, -v80
	v_mul_f32_e32 v78, v77, v77
	v_fmac_f32_e32 v81, 0xb102e308, v74
	v_fmamk_f32 v79, v78, 0x3e9b6dac, v126
	v_sub_f32_e32 v74, v77, v76
	v_add_f32_e32 v102, v80, v81
	v_fmaak_f32 v79, v78, v79, 0x3f2aaada
	v_sub_f32_e32 v74, v75, v74
	v_sub_f32_e32 v75, v102, v80
	v_mul_f32_e32 v76, v77, v78
	v_sub_f32_e32 v103, v81, v75
	v_ldexp_f32 v75, v77, 1
	v_mul_f32_e32 v76, v76, v79
	v_add_f32_e32 v77, v75, v76
	v_sub_f32_e32 v75, v77, v75
	v_ldexp_f32 v74, v74, 1
	v_sub_f32_e32 v75, v76, v75
	v_add_f32_e32 v74, v74, v75
	v_add_f32_e32 v104, v77, v74
	v_sub_f32_e32 v75, v104, v77
	v_ashrrev_i32_e32 v85, 31, v84
	v_sub_f32_e32 v105, v74, v75
	v_lshl_add_u64 v[74:75], s[44:45], 0, v[84:85]
	v_lshlrev_b64 v[74:75], 11, v[74:75]
	v_lshl_add_u64 v[74:75], s[10:11], 0, v[74:75]
	v_lshlrev_b32_e32 v76, 1, v92
	v_mov_b32_e32 v77, v115
	v_lshl_add_u64 v[116:117], v[74:75], 0, v[76:77]
	v_lshlrev_b32_e32 v74, 2, v91
	v_mov_b32_e32 v75, v115
	v_lshl_add_u64 v[74:75], s[44:45], 0, v[74:75]
	v_lshlrev_b64 v[74:75], 11, v[74:75]
	v_lshl_add_u64 v[74:75], s[28:29], 0, v[74:75]
	v_lshlrev_b32_e32 v76, 1, v114
	v_add_co_u32_e32 v78, vcc, s57, v116
	v_lshl_add_u64 v[118:119], v[74:75], 0, v[76:77]
	s_nop 0
	v_addc_co_u32_e32 v79, vcc, 0, v117, vcc
	v_add_co_u32_e32 v86, vcc, s0, v118
	s_mov_b32 s0, 0x8000
	s_nop 0
	v_addc_co_u32_e32 v87, vcc, 0, v119, vcc
	v_add_co_u32_e32 v92, vcc, s0, v118
	global_load_dwordx4 v[74:77], v[116:117], off
	v_mov_b32_e32 v176, 0
	global_load_short_d16_hi v176, v[118:119], off
	v_mov_b32_e32 v173, 0
	global_load_short_d16_hi v173, v[118:119], off offset:2048
	v_addc_co_u32_e32 v93, vcc, 0, v119, vcc
	v_add_co_u32_e32 v94, vcc, s60, v118
	global_load_dwordx4 v[78:81], v[78:79], off
	s_nop 0
	v_mov_b32_e32 v177, 0
	global_load_short_d16_hi v177, v[86:87], off
	v_mov_b32_e32 v174, 0
	global_load_short_d16_hi v174, v[86:87], off offset:2048
	v_mov_b32_e32 v167, 0
	global_load_short_d16_hi v167, v[92:93], off offset:2048
	v_addc_co_u32_e32 v95, vcc, 0, v119, vcc
	v_add_co_u32_e32 v86, vcc, s57, v118
	v_add_f32_e32 v106, v102, v104
	s_nop 0
	v_addc_co_u32_e32 v87, vcc, 0, v119, vcc
	v_add_co_u32_e32 v92, vcc, s61, v118
	v_sub_f32_e32 v107, v106, v102
	s_nop 0
	v_addc_co_u32_e32 v93, vcc, 0, v119, vcc
	v_add_co_u32_e32 v96, vcc, s66, v118
	v_sub_f32_e32 v108, v106, v107
	s_nop 0
	v_addc_co_u32_e32 v97, vcc, 0, v119, vcc
	v_add_co_u32_e32 v98, vcc, s67, v118
	v_sub_f32_e32 v85, v102, v108
	s_nop 0
	v_addc_co_u32_e32 v99, vcc, 0, v119, vcc
	v_mov_b32_e32 v178, 0
	global_load_short_d16_hi v178, v[94:95], off offset:-4096
	v_mov_b32_e32 v175, 0
	global_load_short_d16_hi v175, v[94:95], off
	v_mov_b32_e32 v172, 0
	global_load_short_d16_hi v172, v[94:95], off offset:2048
	v_mov_b32_e32 v168, 0
	global_load_short_d16_hi v168, v[92:93], off offset:-4096
	v_mov_b32_e32 v166, 0
	global_load_short_d16_hi v166, v[86:87], off offset:2048
	v_mov_b32_e32 v165, 0
; #define GAS __attribute__((address_space(1)))
; #define LAS __attribute__((address_space(3)))
; __device__ __forceinline__ void lru_unit(Frame& F, int seq, int n) {
;     ...
;     v4u xr0, xr1; unsigned short zc[16], zn[16];
;     const bf16* xsrc = XA + (rowbase + ct) * DM + c0; const bf16* zsrc = ZA + (rowbase + 4 * tq) * DM + dg;
;     xr0 = *(const GAS v4u*)(xsrc); xr1 = *(const GAS v4u*)(xsrc + (size_t)32 * DM);
; #pragma unroll
;     for (int i = 0; i < 16; ++i) zc[i] = *(const GAS unsigned short*)(zsrc + (size_t)(16 * (i >> 2) + (i & 3)) * DM);
;     for (int t0 = 0; t0 < T; t0 += 64) {
;         *(LAS v4u*)(RAW + ct * 136 + 8 * cg) = xr0; *(LAS v4u*)(RAW + (ct + 32) * 136 + 8 * cg) = xr1;
;         { const int tn = (t0 + 64 < T) ? t0 + 64 : t0;
;           xr0 = *(const GAS v4u*)(xsrc + (size_t)tn * DM); xr1 = *(const GAS v4u*)(xsrc + (size_t)(tn + 32) * DM);
; #pragma unroll
;           for (int i = 0; i < 16; ++i) zn[i] = *(const GAS unsigned short*)(zsrc + (size_t)(tn + 16 * (i >> 2) + (i & 3)) * DM); }
	global_load_short_d16_hi v165, v[92:93], off
	v_mov_b32_e32 v161, 0
	global_load_short_d16_hi v161, v[92:93], off offset:2048
	v_mov_b32_e32 v154, 0
	global_load_short_d16_hi v154, v[96:97], off offset:2048
	v_mov_b32_e32 v159, 0
	global_load_short_d16_hi v159, v[98:99], off offset:-4096
	v_mov_b32_e32 v152, 0
	global_load_short_d16_hi v152, v[98:99], off
	v_mov_b32_e32 v150, 0
	global_load_short_d16_hi v150, v[98:99], off offset:2048
	v_sub_f32_e32 v86, v104, v107
	v_add_f32_e32 v85, v86, v85
	v_add_f32_e32 v86, v103, v105
	v_sub_f32_e32 v87, v86, v103
	v_sub_f32_e32 v92, v86, v87
	v_add_f32_e32 v85, v86, v85
	v_sub_f32_e32 v92, v103, v92
	v_sub_f32_e32 v87, v105, v87
	v_add_f32_e32 v86, v106, v85
	v_add_f32_e32 v87, v87, v92
	v_sub_f32_e32 v92, v86, v106
	v_sub_f32_e32 v85, v85, v92
	v_add_f32_e32 v85, v87, v85
	v_add_f32_e32 v85, v86, v85
	v_cmp_neq_f32_e32 vcc, s35, v101
	v_add_u32_e32 v86, 0, v145
	v_lshl_add_u32 v92, v82, 2, 0
	v_cndmask_b32_e32 v85, v127, v85, vcc
	v_cmp_lt_f32_e64 vcc, |v101|, s56
	v_add_u32_e32 v82, 0, v151
	s_and_b32 s0, s86, 7
	v_cndmask_b32_e32 v85, v85, v101, vcc
	v_add_f32_e32 v85, v100, v85
	v_mul_f32_e32 v147, 0xc138aa3b, v85
	v_lshlrev_b32_e32 v85, 1, v90
	v_cmp_lt_i32_e32 vcc, 2, v84
	v_add3_u32 v148, 0, v83, v85
	s_lshl_b32 s2, s0, 7
	v_cndmask_b32_e32 v83, v128, v129, vcc
	v_cmp_lt_i32_e32 vcc, 1, v84
	v_add3_u32 v153, v86, v83, v85
	s_lshl_b64 s[0:1], s[44:45], 12
	v_cndmask_b32_e32 v83, v130, v131, vcc
	v_cmp_lt_i32_e32 vcc, 0, v84
	v_add3_u32 v155, v86, v83, v85
	v_lshl_add_u32 v87, v90, 2, 0
	v_cndmask_b32_e32 v83, v132, v133, vcc
	v_cmp_gt_i32_e32 vcc, 0, v84
	v_add3_u32 v156, v86, v83, v85
	v_sub_u32_e32 v149, v87, v85
	v_cndmask_b32_e32 v83, v134, v135, vcc
	v_cmp_lt_i32_e32 vcc, s69, v84
	v_add3_u32 v157, v86, v83, v85
	v_mul_lo_u32 v93, v84, s68
	v_cndmask_b32_e32 v83, v128, v129, vcc
	v_cmp_lt_i32_e32 vcc, s70, v84
	v_add3_u32 v158, v82, v83, v85
	v_mov_b32_e32 v83, v115
	v_cndmask_b32_e32 v82, v136, v137, vcc
	v_cmp_lt_i32_e32 vcc, s71, v84
	v_add3_u32 v160, v86, v82, v85
	v_lshl_add_u32 v90, v91, 4, 0
	v_cndmask_b32_e32 v82, v138, v139, vcc
	v_cmp_lt_i32_e32 vcc, s76, v84
	v_add3_u32 v162, v86, v82, v85
	v_cmp_lt_u32_e64 s[6:7], 1, v91
	v_cndmask_b32_e32 v82, v140, v141, vcc
	v_add3_u32 v163, v86, v82, v85
	v_or_b32_e32 v82, v89, v121
	v_lshl_or_b32 v164, v82, 2, v142
	v_lshlrev_b32_e32 v82, 8, v88
	v_and_b32_e32 v120, 0x3000, v82
	v_lshlrev_b32_e32 v82, 10, v88
	v_and_b32_e32 v82, 0xc000, v82
	v_lshl_add_u64 v[82:83], v[82:83], 0, s[0:1]
	s_add_i32 s0, s3, s2
	v_add_u32_e32 v84, s0, v89
	v_mov_b32_e32 v85, v115
	v_mul_u32_u24_e32 v94, 0x110, v89
	v_mul_u32_u24_e32 v91, 0x840, v91
	v_lshl_add_u64 v[82:83], v[84:85], 1, v[82:83]
	s_mov_b32 s37, 0
	v_lshl_add_u64 v[122:123], s[74:75], 0, v[82:83]
	s_mov_b64 s[0:1], 0
	v_add_u32_e32 v169, v87, v93
	v_add_u32_e32 v170, v90, v94
	v_add_u32_e32 v171, v92, v91
	v_mov_b32_e32 v179, 0
	v_mov_b32_e32 v180, 0
	v_mov_b32_e32 v181, 0
	v_mov_b32_e32 v182, 0
	v_mov_b32_e32 v183, 0
	v_mov_b32_e32 v184, 0
	v_mov_b32_e32 v185, 0
	v_mov_b32_e32 v186, 0
	v_mov_b32_e32 v187, 0
	v_mov_b32_e32 v188, 0
	v_mov_b32_e32 v189, 0
	v_mov_b32_e32 v190, 0
	v_mov_b32_e32 v191, 0
	v_mov_b32_e32 v192, 0
	v_mov_b32_e32 v193, 0
	v_mov_b32_e32 v194, 0
.LBB0_438:
	s_cmpk_lt_u32 s37, 0x7c0
	s_cselect_b64 s[44:45], -1, 0
	s_and_b64 s[46:47], s[40:41], s[44:45]
	s_mov_b32 s2, s37
	s_xor_b64 s[44:45], s[46:47], -1
	s_add_i32 s37, s37, 64
	s_and_b64 s[46:47], s[46:47], exec
	s_cselect_b32 s30, s37, s2
	s_lshl_b64 s[46:47], s[30:31], 11
	s_waitcnt vmcnt(17)
	ds_write_b128 v148, v[74:77] offset:17408
	s_waitcnt vmcnt(14)
	ds_write_b128 v148, v[78:81] offset:26112
	v_lshl_add_u64 v[74:75], v[116:117], 0, s[46:47]
	v_lshl_add_u64 v[82:83], v[118:119], 0, s[46:47]
	s_or_b32 s46, s30, 1
	s_mov_b32 s47, s31
	s_lshl_b64 s[46:47], s[46:47], 11
	v_lshl_add_u64 v[84:85], v[118:119], 0, s[46:47]
	s_or_b32 s46, s30, 2
	s_mov_b32 s47, s31
	s_lshl_b64 s[46:47], s[46:47], 11
	v_lshl_add_u64 v[86:87], v[118:119], 0, s[46:47]
	s_or_b32 s46, s30, 3
	s_mov_b32 s47, s31
	s_lshl_b64 s[46:47], s[46:47], 11
	v_lshl_add_u64 v[88:89], v[118:119], 0, s[46:47]
	s_or_b32 s46, s30, 16
	s_mov_b32 s47, s31
	s_lshl_b64 s[46:47], s[46:47], 11
	v_lshl_add_u64 v[90:91], v[118:119], 0, s[46:47]
	s_or_b32 s46, s30, 17
	s_mov_b32 s47, s31
	s_lshl_b64 s[46:47], s[46:47], 11
	v_lshl_add_u64 v[92:93], v[118:119], 0, s[46:47]
	s_or_b32 s46, s30, 18
	s_mov_b32 s47, s31
	s_lshl_b64 s[46:47], s[46:47], 11
	v_lshl_add_u64 v[94:95], v[118:119], 0, s[46:47]
	s_or_b32 s46, s30, 19
	s_mov_b32 s47, s31
	s_or_b32 s88, s30, 32
	s_mov_b32 s89, s31
	s_lshl_b64 s[46:47], s[46:47], 11
	s_lshl_b64 s[88:89], s[88:89], 11
	v_lshl_add_u64 v[96:97], v[118:119], 0, s[46:47]
	s_or_b32 s46, s30, 33
	s_mov_b32 s47, s31
	v_lshl_add_u64 v[78:79], v[116:117], 0, s[88:89]
	s_lshl_b64 s[46:47], s[46:47], 11
	global_load_dwordx4 v[74:77], v[74:75], off
	s_nop 0
	global_load_dwordx4 v[78:81], v[78:79], off
	s_nop 0
	global_load_short_d16_hi v179, v[82:83], off
	global_load_short_d16_hi v180, v[84:85], off
	global_load_short_d16_hi v181, v[86:87], off
	global_load_short_d16_hi v182, v[88:89], off
	global_load_short_d16_hi v183, v[90:91], off
	global_load_short_d16_hi v184, v[92:93], off
	global_load_short_d16_hi v185, v[94:95], off
	global_load_short_d16_hi v186, v[96:97], off
	v_lshl_add_u64 v[84:85], v[118:119], 0, s[46:47]
	s_or_b32 s46, s30, 34
	s_mov_b32 s47, s31
	s_lshl_b64 s[46:47], s[46:47], 11
	v_lshl_add_u64 v[86:87], v[118:119], 0, s[46:47]
	s_or_b32 s46, s30, 35
	s_mov_b32 s47, s31
	s_lshl_b64 s[46:47], s[46:47], 11
	v_lshl_add_u64 v[88:89], v[118:119], 0, s[46:47]
	s_or_b32 s46, s30, 48
	s_mov_b32 s47, s31
	s_lshl_b64 s[46:47], s[46:47], 11
	v_lshl_add_u64 v[90:91], v[118:119], 0, s[46:47]
	s_or_b32 s46, s30, 49
	s_mov_b32 s47, s31
	s_lshl_b64 s[46:47], s[46:47], 11
	v_lshl_add_u64 v[92:93], v[118:119], 0, s[46:47]
	s_or_b32 s46, s30, 50
	s_mov_b32 s47, s31
	s_lshl_b64 s[46:47], s[46:47], 11
	s_or_b32 s30, s30, 51
	v_lshl_add_u64 v[82:83], v[118:119], 0, s[88:89]
	v_lshl_add_u64 v[94:95], v[118:119], 0, s[46:47]
	s_lshl_b64 s[46:47], s[30:31], 11
	v_lshl_add_u64 v[96:97], v[118:119], 0, s[46:47]
	global_load_short_d16_hi v187, v[82:83], off
	global_load_short_d16_hi v188, v[84:85], off
	global_load_short_d16_hi v189, v[86:87], off
	global_load_short_d16_hi v190, v[88:89], off
	global_load_short_d16_hi v191, v[90:91], off
	global_load_short_d16_hi v192, v[92:93], off
	global_load_short_d16_hi v193, v[94:95], off
	global_load_short_d16_hi v194, v[96:97], off
	s_waitcnt lgkmcnt(0)
	s_barrier
; #define LAS __attribute__((address_space(3)))
; __device__ __forceinline__ v4u pack8(const float* v) { v4u w; w.x = pk2(v[0], v[1]); w.y = pk2(v[2], v[3]); w.z = pk2(v[4], v[5]); w.w = pk2(v[6], v[7]); return w; }
; __device__ __forceinline__ void lru_unit(Frame& F, int seq, int n) {
;     ...
; #pragma unroll
;         for (int p = 0; p < 2; ++p) {
;             const int t = ct + 32 * p;
;             float a[8];
; #pragma unroll
;             for (int e = 0; e < 8; ++e) a[e] = cbias[e];
; #pragma unroll
;             for (int j = 0; j < 4; ++j) {
;                 const int tr = t + j - 3;
;                 const v4u q = (tr >= 0) ? *(const LAS v4u*)(RAW + tr * 136 + 8 * cg) : *(const LAS v4u*)(HALO + (tr + 3) * 136 + 8 * cg);
;                 const float x[8] = {bflo(q.x), bfhi(q.x), bflo(q.y), bfhi(q.y), bflo(q.z), bfhi(q.z), bflo(q.w), bfhi(q.w)};
; #pragma unroll
;                 for (int e = 0; e < 8; ++e) a[e] += x[e] * cw[j][e];
;             }
;             *(LAS f32x4*)(BB + t * 132 + 8 * cg) = (f32x4){a[0], a[1], a[2], a[3]}; *(LAS f32x4*)(BB + t * 132 + 8 * cg + 4) = (f32x4){a[4], a[5], a[6], a[7]};
;             *(LAS v4u*)(XCB + t * 136 + 8 * cg) = pack8(a);
;         }
;         if (tid < 48) *(LAS v4u*)(HALO + (tid >> 4) * 136 + 8 * cg) = *(const LAS v4u*)(RAW + (61 + (tid >> 4)) * 136 + 8 * cg);
	ds_read_b128 v[82:85], v153
	ds_read_b128 v[86:89], v155
	ds_read_b128 v[90:93], v156
	ds_read_b128 v[94:97], v157
	s_waitcnt lgkmcnt(3)
	v_lshlrev_b32_e32 v98, 16, v82
	v_and_b32_e32 v99, 0xffff0000, v82
	v_lshlrev_b32_e32 v82, 16, v83
	v_and_b32_e32 v83, 0xffff0000, v83
	v_pk_fma_f32 v[98:99], v[14:15], v[98:99], v[10:11]
	s_waitcnt lgkmcnt(2)
	v_lshlrev_b32_e32 v100, 16, v86
	v_and_b32_e32 v101, 0xffff0000, v86
	v_pk_fma_f32 v[82:83], v[16:17], v[82:83], v[12:13]
	v_lshlrev_b32_e32 v86, 16, v87
	v_and_b32_e32 v87, 0xffff0000, v87
	v_pk_fma_f32 v[98:99], v[18:19], v[100:101], v[98:99]
	s_waitcnt lgkmcnt(1)
	v_lshlrev_b32_e32 v100, 16, v90
	v_and_b32_e32 v101, 0xffff0000, v90
	v_pk_fma_f32 v[82:83], v[20:21], v[86:87], v[82:83]
	v_lshlrev_b32_e32 v86, 16, v91
	v_and_b32_e32 v87, 0xffff0000, v91
	v_pk_fma_f32 v[98:99], v[22:23], v[100:101], v[98:99]
	s_waitcnt lgkmcnt(0)
	v_lshlrev_b32_e32 v100, 16, v94
	v_and_b32_e32 v101, 0xffff0000, v94
	v_pk_fma_f32 v[82:83], v[24:25], v[86:87], v[82:83]
	v_lshlrev_b32_e32 v86, 16, v95
	v_and_b32_e32 v87, 0xffff0000, v95
	v_pk_fma_f32 v[98:99], v[34:35], v[100:101], v[98:99]
	v_pk_fma_f32 v[100:101], v[36:37], v[86:87], v[82:83]
	v_lshlrev_b32_e32 v82, 16, v84
	v_and_b32_e32 v83, 0xffff0000, v84
	v_pk_fma_f32 v[82:83], v[6:7], v[82:83], v[2:3]
	v_lshlrev_b32_e32 v86, 16, v88
	v_and_b32_e32 v87, 0xffff0000, v88
	v_pk_fma_f32 v[82:83], v[26:27], v[86:87], v[82:83]
	v_lshlrev_b32_e32 v86, 16, v92
	v_and_b32_e32 v87, 0xffff0000, v92
	v_pk_fma_f32 v[82:83], v[30:31], v[86:87], v[82:83]
	v_lshlrev_b32_e32 v86, 16, v96
	v_and_b32_e32 v87, 0xffff0000, v96
	v_lshlrev_b32_e32 v84, 16, v85
	v_and_b32_e32 v85, 0xffff0000, v85
	v_pk_fma_f32 v[82:83], v[38:39], v[86:87], v[82:83]
	v_pk_fma_f32 v[84:85], v[8:9], v[84:85], v[4:5]
	v_lshlrev_b32_e32 v86, 16, v89
	v_and_b32_e32 v87, 0xffff0000, v89
	v_pk_fma_f32 v[84:85], v[28:29], v[86:87], v[84:85]
	v_lshlrev_b32_e32 v86, 16, v93
	v_and_b32_e32 v87, 0xffff0000, v93
	v_pk_fma_f32 v[84:85], v[32:33], v[86:87], v[84:85]
	v_lshlrev_b32_e32 v86, 16, v97
	v_and_b32_e32 v87, 0xffff0000, v97
	v_pk_fma_f32 v[84:85], v[40:41], v[86:87], v[84:85]
	ds_write_b128 v169, v[98:101] offset:35840
	ds_write_b128 v169, v[82:85] offset:35856
	v_cvt_pk_bf16_f32 v86, v98, v99
	v_cvt_pk_bf16_f32 v87, v100, v101
	v_cvt_pk_bf16_f32 v88, v82, v83
	v_add_u32_e32 v82, v149, v145
	v_cvt_pk_bf16_f32 v89, v84, v85
	ds_write_b128 v82, v[86:89]
	ds_read_b128 v[82:85], v158
	ds_read_b128 v[86:89], v160
	ds_read_b128 v[90:93], v162
	ds_read_b128 v[94:97], v163
	s_waitcnt lgkmcnt(3)
	v_lshlrev_b32_e32 v98, 16, v82
	v_and_b32_e32 v99, 0xffff0000, v82
	v_lshlrev_b32_e32 v82, 16, v83
	v_and_b32_e32 v83, 0xffff0000, v83
	v_pk_fma_f32 v[98:99], v[14:15], v[98:99], v[10:11]
	s_waitcnt lgkmcnt(2)
	v_lshlrev_b32_e32 v100, 16, v86
	v_and_b32_e32 v101, 0xffff0000, v86
	v_pk_fma_f32 v[82:83], v[16:17], v[82:83], v[12:13]
	v_lshlrev_b32_e32 v86, 16, v87
	v_and_b32_e32 v87, 0xffff0000, v87
	v_pk_fma_f32 v[98:99], v[18:19], v[100:101], v[98:99]
	s_waitcnt lgkmcnt(1)
	v_lshlrev_b32_e32 v100, 16, v90
	v_and_b32_e32 v101, 0xffff0000, v90
	v_pk_fma_f32 v[82:83], v[20:21], v[86:87], v[82:83]
	v_lshlrev_b32_e32 v86, 16, v91
	v_and_b32_e32 v87, 0xffff0000, v91
	v_pk_fma_f32 v[98:99], v[22:23], v[100:101], v[98:99]
	s_waitcnt lgkmcnt(0)
	v_lshlrev_b32_e32 v100, 16, v94
	v_and_b32_e32 v101, 0xffff0000, v94
	v_pk_fma_f32 v[82:83], v[24:25], v[86:87], v[82:83]
	v_lshlrev_b32_e32 v86, 16, v95
	v_and_b32_e32 v87, 0xffff0000, v95
	v_pk_fma_f32 v[98:99], v[34:35], v[100:101], v[98:99]
	v_pk_fma_f32 v[100:101], v[36:37], v[86:87], v[82:83]
	v_lshlrev_b32_e32 v82, 16, v84
	v_and_b32_e32 v83, 0xffff0000, v84
	v_pk_fma_f32 v[82:83], v[6:7], v[82:83], v[2:3]
	v_lshlrev_b32_e32 v86, 16, v88
	v_and_b32_e32 v87, 0xffff0000, v88
	v_pk_fma_f32 v[82:83], v[26:27], v[86:87], v[82:83]
	v_lshlrev_b32_e32 v86, 16, v92
	v_and_b32_e32 v87, 0xffff0000, v92
	v_pk_fma_f32 v[82:83], v[30:31], v[86:87], v[82:83]
	v_lshlrev_b32_e32 v86, 16, v96
	v_and_b32_e32 v87, 0xffff0000, v96
	v_lshlrev_b32_e32 v84, 16, v85
	v_and_b32_e32 v85, 0xffff0000, v85
	v_pk_fma_f32 v[82:83], v[38:39], v[86:87], v[82:83]
	v_pk_fma_f32 v[84:85], v[8:9], v[84:85], v[4:5]
	v_lshlrev_b32_e32 v86, 16, v89
	v_and_b32_e32 v87, 0xffff0000, v89
	v_pk_fma_f32 v[84:85], v[28:29], v[86:87], v[84:85]
	v_lshlrev_b32_e32 v86, 16, v93
	v_and_b32_e32 v87, 0xffff0000, v93
	v_pk_fma_f32 v[84:85], v[32:33], v[86:87], v[84:85]
	v_lshlrev_b32_e32 v86, 16, v97
	v_and_b32_e32 v87, 0xffff0000, v97
	v_pk_fma_f32 v[84:85], v[40:41], v[86:87], v[84:85]
	ds_write_b128 v169, v[98:101] offset:52736
	ds_write_b128 v169, v[82:85] offset:52752
	v_cvt_pk_bf16_f32 v86, v98, v99
	v_cvt_pk_bf16_f32 v87, v100, v101
	v_cvt_pk_bf16_f32 v88, v82, v83
	v_add_u32_e32 v82, v149, v151
	v_cvt_pk_bf16_f32 v89, v84, v85
	ds_write_b128 v82, v[86:89]
	s_and_saveexec_b64 s[46:47], s[8:9]
	s_cbranch_execz .LBB0_440
	ds_read_b128 v[82:85], v148 offset:34000
	s_waitcnt lgkmcnt(0)
	ds_write_b128 v148, v[82:85] offset:34816
; #define LAS __attribute__((address_space(3)))
; __device__ __forceinline__ float sigm(float v) { return __builtin_amdgcn_rcpf(1.f + __builtin_amdgcn_exp2f(-LOG2E * v)); }
; __device__ __forceinline__ void lru_unit(Frame& F, int seq, int n) {
;     ...
;         {
;             pg8::f32x4 ar[4], ai_[4];
; #pragma unroll
;             for (int tt = 0; tt < 4; ++tt) { ar[tt] = (pg8::f32x4){0.f, 0.f, 0.f, 0.f}; ai_[tt] = (pg8::f32x4){0.f, 0.f, 0.f, 0.f}; }
; #pragma unroll
;             for (int tt = 0; tt < 4; ++tt)
; #pragma unroll
;                 for (int kk = 0; kk < 4; ++kk) {
;                     const bf16x8 af = *(const LAS bf16x8*)(XCB + (16 * tt + (lane & 15)) * 136 + 32 * kk + 8 * tq);
;                     ar[tt] = __builtin_amdgcn_mfma_f32_16x16x32_bf16(af, Br[kk], ar[tt], 0, 0, 0);
;                     ai_[tt] = __builtin_amdgcn_mfma_f32_16x16x32_bf16(af, Bi[kk], ai_[tt], 0, 0, 0);
;                 }
;             float A[4][4], B[4][4];
; #pragma unroll
;             for (int tt = 0; tt < 4; ++tt)
; #pragma unroll
;                 for (int rg = 0; rg < 4; ++rg) {
;                     const int t = 16 * tt + 4 * tq + rg;
;                     const float r = sigm(ar[tt][rg] + brg), ig = sigm(ai_[tt][rg] + big);
;                     const float av = __builtin_amdgcn_exp2f(r * nsp);
;                     float mult = __builtin_amdgcn_sqrtf(fmaxf(__builtin_fmaf(-av, av, 1.f), 0.f));
;                     if (!smp && (t0 + t) == 0) mult = 1.f;
;                     A[tt][rg] = av; B[tt][rg] = mult * ig * BB[t * 132 + dl];
.LBB0_440:
	s_or_b64 exec, exec, s[46:47]
	s_waitcnt lgkmcnt(0)
	s_barrier
	ds_read_b128 v[82:85], v170
	ds_read_b128 v[90:93], v170 offset:64
	s_waitcnt lgkmcnt(1)
	v_mfma_f32_16x16x32_bf16 v[86:89], v[82:85], v[42:45], 0
	ds_read_b128 v[196:199], v170 offset:13120
	v_mfma_f32_16x16x32_bf16 v[82:85], v[82:85], v[66:69], 0
	s_waitcnt lgkmcnt(1)
	v_mfma_f32_16x16x32_bf16 v[86:89], v[90:93], v[46:49], v[86:89]
	v_mfma_f32_16x16x32_bf16 v[82:85], v[90:93], v[50:53], v[82:85]
	ds_read_b128 v[90:93], v170 offset:128
	s_waitcnt lgkmcnt(0)
	v_mfma_f32_16x16x32_bf16 v[86:89], v[90:93], v[58:61], v[86:89]
	v_mfma_f32_16x16x32_bf16 v[82:85], v[90:93], v[54:57], v[82:85]
	ds_read_b128 v[90:93], v170 offset:192
	s_waitcnt lgkmcnt(0)
	v_mfma_f32_16x16x32_bf16 v[106:109], v[90:93], v[70:73], v[82:85]
	s_nop 4
	ds_read_b128 v[82:85], v170 offset:4352
	s_nop 1
	v_fma_f32 v106, v106, s90, v144
	v_mfma_f32_16x16x32_bf16 v[110:113], v[90:93], v[62:65], v[86:89]
	ds_read_b128 v[90:93], v170 offset:4416
	s_nop 0
	v_exp_f32_e32 v106, v106
	s_waitcnt lgkmcnt(1)
	v_mfma_f32_16x16x32_bf16 v[86:89], v[82:85], v[42:45], 0
	v_fma_f32 v107, v107, s90, v144
	s_nop 1
	v_fma_f32 v110, v110, s90, v143
	s_nop 0
	v_mfma_f32_16x16x32_bf16 v[82:85], v[82:85], v[66:69], 0
	v_exp_f32_e32 v110, v110
	v_add_f32_e32 v106, 1.0, v106
	v_rcp_f32_e32 v106, v106
	s_waitcnt lgkmcnt(0)
	v_mfma_f32_16x16x32_bf16 v[86:89], v[90:93], v[46:49], v[86:89]
	v_add_f32_e32 v110, 1.0, v110
	v_rcp_f32_e32 v110, v110
	s_nop 0
	v_mfma_f32_16x16x32_bf16 v[82:85], v[90:93], v[50:53], v[82:85]
	ds_read_b128 v[90:93], v170 offset:4480
	v_mul_f32_e32 v110, v147, v110
	v_exp_f32_e32 v110, v110
	s_waitcnt lgkmcnt(0)
	v_mfma_f32_16x16x32_bf16 v[86:89], v[90:93], v[58:61], v[86:89]
	v_fma_f32 v195, -v110, v110, 1.0 clamp
	s_nop 0
	v_sqrt_f32_e32 v195, v195
	v_mfma_f32_16x16x32_bf16 v[82:85], v[90:93], v[54:57], v[82:85]
	ds_read_b128 v[90:93], v170 offset:4544
	v_exp_f32_e32 v107, v107
	v_fma_f32 v109, v109, s90, v144
	s_waitcnt lgkmcnt(0)
	v_mfma_f32_16x16x32_bf16 v[98:101], v[90:93], v[70:73], v[82:85]
	s_nop 2
	ds_read_b128 v[82:85], v170 offset:8704
	v_add_f32_e32 v107, 1.0, v107
	v_rcp_f32_e32 v107, v107
	v_mfma_f32_16x16x32_bf16 v[102:105], v[90:93], v[62:65], v[86:89]
	ds_read_b128 v[90:93], v170 offset:8768
	s_nop 0
	v_exp_f32_e32 v109, v109
	s_waitcnt lgkmcnt(1)
	v_mfma_f32_16x16x32_bf16 v[86:89], v[82:85], v[42:45], 0
	v_add_f32_e32 v109, 1.0, v109
	s_nop 1
	v_fma_f32 v102, v102, s90, v143
	s_nop 0
	v_mfma_f32_16x16x32_bf16 v[82:85], v[82:85], v[66:69], 0
	v_exp_f32_e32 v102, v102
	v_rcp_f32_e32 v109, v109
	v_fma_f32 v98, v98, s90, v144
	s_waitcnt lgkmcnt(0)
	v_mfma_f32_16x16x32_bf16 v[86:89], v[90:93], v[46:49], v[86:89]
	v_add_f32_e32 v102, 1.0, v102
	v_rcp_f32_e32 v102, v102
	s_nop 0
	v_mfma_f32_16x16x32_bf16 v[82:85], v[90:93], v[50:53], v[82:85]
	ds_read_b128 v[90:93], v170 offset:8832
	v_mul_f32_e32 v102, v147, v102
	v_exp_f32_e32 v98, v98
	s_waitcnt lgkmcnt(0)
	v_mfma_f32_16x16x32_bf16 v[86:89], v[90:93], v[58:61], v[86:89]
	v_add_f32_e32 v98, 1.0, v98
	v_rcp_f32_e32 v98, v98
	v_fma_f32 v99, v99, s90, v144
	v_mfma_f32_16x16x32_bf16 v[82:85], v[90:93], v[54:57], v[82:85]
	ds_read_b128 v[90:93], v170 offset:8896
	s_nop 0
	v_exp_f32_e32 v99, v99
	s_waitcnt lgkmcnt(0)
	v_mfma_f32_16x16x32_bf16 v[94:97], v[90:93], v[62:65], v[86:89]
	v_add_f32_e32 v99, 1.0, v99
	v_rcp_f32_e32 v99, v99
	v_fma_f32 v101, v101, s90, v144
	v_mfma_f32_16x16x32_bf16 v[90:93], v[90:93], v[70:73], v[82:85]
	s_nop 3
	v_fma_f32 v94, v94, s90, v143
	s_nop 0
	v_exp_f32_e32 v94, v94
	ds_read_b128 v[82:85], v170 offset:13056
	s_waitcnt lgkmcnt(0)
	v_mfma_f32_16x16x32_bf16 v[86:89], v[82:85], v[42:45], 0
	v_add_f32_e32 v94, 1.0, v94
	v_rcp_f32_e32 v94, v94
	v_fma_f32 v90, v90, s90, v144
	v_mfma_f32_16x16x32_bf16 v[82:85], v[82:85], v[66:69], 0
	s_nop 0
	v_mul_f32_e32 v94, v147, v94
	v_exp_f32_e32 v90, v90
	v_mfma_f32_16x16x32_bf16 v[86:89], v[196:199], v[46:49], v[86:89]
	s_nop 0
	v_exp_f32_e32 v101, v101
	v_add_f32_e32 v90, 1.0, v90
	v_mfma_f32_16x16x32_bf16 v[82:85], v[196:199], v[50:53], v[82:85]
	ds_read_b128 v[196:199], v170 offset:13184
	v_rcp_f32_e32 v90, v90
	v_add_f32_e32 v101, 1.0, v101
	s_waitcnt lgkmcnt(0)
	v_mfma_f32_16x16x32_bf16 v[86:89], v[196:199], v[58:61], v[86:89]
	v_rcp_f32_e32 v206, v101
	v_fma_f32 v91, v91, s90, v144
	s_nop 0
	v_mfma_f32_16x16x32_bf16 v[82:85], v[196:199], v[54:57], v[82:85]
	ds_read_b128 v[196:199], v170 offset:13248
	v_exp_f32_e32 v91, v91
	v_fma_f32 v93, v93, s90, v144
	s_waitcnt lgkmcnt(0)
	v_mfma_f32_16x16x32_bf16 v[86:89], v[196:199], v[62:65], v[86:89]
	v_add_f32_e32 v91, 1.0, v91
	v_rcp_f32_e32 v91, v91
	s_nop 0
	v_mfma_f32_16x16x32_bf16 v[82:85], v[196:199], v[70:73], v[82:85]
	v_add_u32_e32 v196, s0, v120
	v_cmp_eq_u32_e32 vcc, 0, v196
	s_and_b64 s[46:47], s[40:41], vcc
	v_cndmask_b32_e64 v195, v195, 1.0, s[46:47]
	v_mul_f32_e32 v106, v106, v195
	v_add_u32_e32 v195, 0x8c00, v171
	ds_read2_b32 v[196:197], v195 offset1:132
	v_fma_f32 v86, v86, s90, v143
	s_nop 0
	v_exp_f32_e32 v86, v86
	v_fma_f32 v82, v82, s90, v144
	s_waitcnt lgkmcnt(0)
; __device__ __forceinline__ float sigm(float v) { return __builtin_amdgcn_rcpf(1.f + __builtin_amdgcn_exp2f(-LOG2E * v)); }
; __device__ __forceinline__ void lru_unit(Frame& F, int seq, int n) {
;     ...
;             for (int tt = 0; tt < 4; ++tt)
; #pragma unroll
;                 for (int rg = 0; rg < 4; ++rg) {
;                     const int t = 16 * tt + 4 * tq + rg;
;                     const float r = sigm(ar[tt][rg] + brg), ig = sigm(ai_[tt][rg] + big);
;                     const float av = __builtin_amdgcn_exp2f(r * nsp);
;                     float mult = __builtin_amdgcn_sqrtf(fmaxf(__builtin_fmaf(-av, av, 1.f), 0.f));
;                     if (!smp && (t0 + t) == 0) mult = 1.f;
;                     A[tt][rg] = av; B[tt][rg] = mult * ig * BB[t * 132 + dl];
;                 }
; #pragma unroll
;             for (int tt = 0; tt < 4; ++tt)
; #pragma unroll
;                 for (int rg = 1; rg < 4; ++rg) { B[tt][rg] = A[tt][rg] * B[tt][rg - 1] + B[tt][rg]; A[tt][rg] = A[tt][rg] * A[tt][rg - 1]; }
	v_mul_f32_e32 v195, v106, v196
	v_fma_f32 v106, v111, s90, v143
	s_nop 0
	v_exp_f32_e32 v106, v106
	v_add_f32_e32 v86, 1.0, v86
	v_rcp_f32_e32 v86, v86
	s_nop 0
	v_add_f32_e32 v106, 1.0, v106
	v_rcp_f32_e32 v106, v106
	v_mul_f32_e32 v86, v147, v86
	v_exp_f32_e32 v82, v82
	v_fma_f32 v83, v83, s90, v144
	v_mul_f32_e32 v106, v147, v106
	v_exp_f32_e32 v196, v106
	v_add_f32_e32 v82, 1.0, v82
	v_rcp_f32_e32 v82, v82
	s_nop 0
	v_fma_f32 v106, -v196, v196, 1.0 clamp
	s_nop 0
	v_sqrt_f32_e32 v106, v106
	v_exp_f32_e32 v83, v83
	v_exp_f32_e32 v93, v93
	v_fma_f32 v92, v92, s90, v144
	v_mul_f32_e32 v106, v107, v106
	v_fma_f32 v107, v108, s90, v144
	v_fma_f32 v108, v113, s90, v143
	s_nop 0
	v_exp_f32_e32 v108, v108
	v_mul_f32_e32 v111, v106, v197
	v_fma_f32 v106, v112, s90, v143
	s_nop 0
	v_add_f32_e32 v108, 1.0, v108
	v_rcp_f32_e32 v108, v108
	v_exp_f32_e32 v106, v106
	s_nop 0
	v_exp_f32_e32 v107, v107
	v_mul_f32_e32 v108, v147, v108
	v_exp_f32_e32 v199, v108
	v_add_f32_e32 v106, 1.0, v106
	v_rcp_f32_e32 v106, v106
	v_add_f32_e32 v83, 1.0, v83
	v_fma_f32 v108, -v199, v199, 1.0 clamp
	s_nop 0
	v_sqrt_f32_e32 v108, v108
	v_mul_f32_e32 v106, v147, v106
	v_exp_f32_e32 v197, v106
	v_add_f32_e32 v107, 1.0, v107
	v_mul_f32_e32 v200, v109, v108
	v_exp_f32_e32 v108, v102
	v_fma_f32 v106, -v197, v197, 1.0 clamp
	s_nop 0
	v_rcp_f32_e32 v107, v107
	v_fma_f32 v102, -v108, v108, 1.0 clamp
	s_nop 0
	v_sqrt_f32_e32 v102, v102
	v_sqrt_f32_e32 v106, v106
	v_fmac_f32_e32 v111, v196, v195
	s_nop 0
	v_mul_f32_e32 v98, v98, v102
	v_add_u32_e32 v102, 0xac00, v171
	ds_read2_b32 v[112:113], v102 offset0:64 offset1:196
	v_fma_f32 v102, v105, s90, v143
	s_nop 0
	v_exp_f32_e32 v102, v102
	v_mul_f32_e32 v198, v107, v106
	s_waitcnt lgkmcnt(0)
	v_mul_f32_e32 v109, v98, v112
	v_fma_f32 v98, v103, s90, v143
	s_nop 0
	v_exp_f32_e32 v98, v98
	v_add_f32_e32 v102, 1.0, v102
	v_rcp_f32_e32 v102, v102
	v_add_u32_e32 v106, 0x9000, v171
	v_add_f32_e32 v98, 1.0, v98
	v_rcp_f32_e32 v98, v98
	v_mul_f32_e32 v101, v147, v102
	v_exp_f32_e32 v101, v101
	ds_read2_b32 v[106:107], v106 offset0:8 offset1:140
	v_mul_f32_e32 v98, v147, v98
	v_exp_f32_e32 v203, v98
	v_add_f32_e32 v93, 1.0, v93
	v_mul_f32_e32 v201, v197, v111
	v_exp_f32_e32 v92, v92
	v_fma_f32 v98, -v203, v203, 1.0 clamp
	s_nop 0
	v_sqrt_f32_e32 v98, v98
	v_rcp_f32_e32 v210, v93
	s_waitcnt lgkmcnt(0)
	v_fmac_f32_e32 v201, v198, v106
	v_mul_f32_e32 v106, v203, v108
	v_mul_f32_e32 v98, v99, v98
	v_mul_f32_e32 v112, v98, v113
	v_fma_f32 v98, v104, s90, v143
	v_exp_f32_e32 v104, v94
	v_exp_f32_e32 v113, v86
	s_nop 0
	v_exp_f32_e32 v98, v98
	v_fma_f32 v94, -v104, v104, 1.0 clamp
	s_nop 0
	v_sqrt_f32_e32 v94, v94
	v_fma_f32 v86, -v113, v113, 1.0 clamp
	s_nop 0
	v_sqrt_f32_e32 v86, v86
	v_mul_f32_e32 v90, v90, v94
	v_add_u32_e32 v94, 0xce00, v171
	ds_read2_b32 v[102:103], v94 offset1:132
	v_mul_f32_e32 v86, v82, v86
	v_add_u32_e32 v82, 0xee00, v171
	v_add_f32_e32 v98, 1.0, v98
	v_rcp_f32_e32 v98, v98
	s_waitcnt lgkmcnt(0)
	v_mul_f32_e32 v105, v90, v102
	v_fma_f32 v90, v95, s90, v143
	s_nop 0
	v_exp_f32_e32 v90, v90
	v_fma_f32 v99, v100, s90, v144
	v_mul_f32_e32 v98, v147, v98
	s_nop 0
	v_add_f32_e32 v90, 1.0, v90
	v_rcp_f32_e32 v90, v90
	v_exp_f32_e32 v100, v98
	v_exp_f32_e32 v99, v99
	v_fmac_f32_e32 v112, v203, v109
	v_mul_f32_e32 v90, v147, v90
	v_exp_f32_e32 v90, v90
	v_fma_f32 v98, -v100, v100, 1.0 clamp
	v_add_f32_e32 v99, 1.0, v99
	s_nop 0
	v_fma_f32 v94, -v90, v90, 1.0 clamp
	s_nop 0
	v_sqrt_f32_e32 v94, v94
	v_rcp_f32_e32 v99, v99
	v_sqrt_f32_e32 v98, v98
	v_add_f32_e32 v92, 1.0, v92
	v_mul_f32_e32 v91, v91, v94
	v_fma_f32 v94, v96, s90, v143
	s_nop 0
	v_exp_f32_e32 v94, v94
	v_mul_f32_e32 v91, v91, v103
	v_mul_f32_e32 v205, v99, v98
	v_add_u32_e32 v98, 0xb000, v171
	v_add_f32_e32 v94, 1.0, v94
	v_rcp_f32_e32 v94, v94
	ds_read2_b32 v[98:99], v98 offset0:72 offset1:204
	v_rcp_f32_e32 v92, v92
	v_fmac_f32_e32 v91, v90, v105
	v_mul_f32_e32 v94, v147, v94
	v_exp_f32_e32 v95, v94
	v_add_u32_e32 v94, 0xd200, v171
	ds_read2_b32 v[102:103], v94 offset0:8 offset1:140
	v_fma_f32 v94, v97, s90, v143
	ds_read2_b32 v[96:97], v82 offset0:64 offset1:196
	v_fma_f32 v82, v87, s90, v143
	s_nop 0
	v_exp_f32_e32 v82, v82
	v_rcp_f32_e32 v87, v83
	v_fma_f32 v83, v84, s90, v144
	s_nop 0
	v_add_f32_e32 v82, 1.0, v82
	v_rcp_f32_e32 v82, v82
	v_exp_f32_e32 v83, v83
	s_nop 0
	v_exp_f32_e32 v94, v94
	v_mul_f32_e32 v82, v147, v82
	v_exp_f32_e32 v204, v82
	v_fma_f32 v82, v88, s90, v143
	s_nop 0
	v_exp_f32_e32 v82, v82
	v_add_f32_e32 v83, 1.0, v83
	v_rcp_f32_e32 v214, v83
	v_fma_f32 v83, v85, s90, v144
	v_add_f32_e32 v82, 1.0, v82
	v_rcp_f32_e32 v82, v82
	s_nop 0
	v_add_f32_e32 v94, 1.0, v94
	v_exp_f32_e32 v83, v83
	v_mul_f32_e32 v82, v147, v82
	v_exp_f32_e32 v207, v82
	v_add_u32_e32 v82, 0xf200, v171
	ds_read2_b32 v[208:209], v82 offset0:72 offset1:204
	v_fma_f32 v82, v89, s90, v143
	s_nop 0
	v_exp_f32_e32 v82, v82
	v_rcp_f32_e32 v94, v94
	v_add_f32_e32 v83, 1.0, v83
	v_rcp_f32_e32 v215, v83
	v_add_f32_e32 v82, 1.0, v82
	v_rcp_f32_e32 v82, v82
	v_mul_f32_e32 v93, v147, v94
	v_mul_f32_e32 v83, v100, v112
	v_exp_f32_e32 v93, v93
	v_mul_f32_e32 v82, v147, v82
	v_exp_f32_e32 v211, v82
	v_fma_f32 v82, -v101, v101, 1.0 clamp
	s_nop 0
	v_sqrt_f32_e32 v82, v82
	s_waitcnt lgkmcnt(3)
	v_fmac_f32_e32 v83, v205, v98
	v_mul_f32_e32 v98, v100, v106
	v_mov_b32_e32 v100, v99
	v_mul_f32_e32 v82, v206, v82
	v_pk_mul_f32 v[84:85], v[82:83], v[100:101]
	v_fma_f32 v88, -v93, v93, 1.0 clamp
	v_add_f32_e32 v99, v84, v85
	v_fma_f32 v84, -v95, v95, 1.0 clamp
	s_nop 0
	v_sqrt_f32_e32 v84, v84
	s_nop 0
	v_sqrt_f32_e32 v88, v88
	v_mul_f32_e32 v82, v90, v104
	s_waitcnt lgkmcnt(2)
; __device__ __forceinline__ void lru_unit(Frame& F, int seq, int n) {
;     ...
; #pragma unroll
;             for (int tt = 0; tt < 4; ++tt)
; #pragma unroll
;                 for (int rg = 1; rg < 4; ++rg) { B[tt][rg] = A[tt][rg] * B[tt][rg - 1] + B[tt][rg]; A[tt][rg] = A[tt][rg] * A[tt][rg - 1]; }
;             float EA[4], EB[4], TA[4], TB[4];
; #pragma unroll
;             for (int tt = 0; tt < 4; ++tt) {
;                 float SA = A[tt][3], SB = B[tt][3];
;                 { const float pA = __shfl_up(SA, 16), pB = __shfl_up(SB, 16); if (tq >= 1) { SB = SA * pB + SB; SA = SA * pA; } }
;                 { const float pA = __shfl_up(SA, 32), pB = __shfl_up(SB, 32); if (tq >= 2) { SB = SA * pB + SB; SA = SA * pA; } }
;                 { const float pA = __shfl_up(SA, 16), pB = __shfl_up(SB, 16); EA[tt] = (tq >= 1) ? pA : 1.f; EB[tt] = (tq >= 1) ? pB : 0.f; }
;                 TA[tt] = __shfl(SA, (lane & 15) + 48); TB[tt] = __shfl(SB, (lane & 15) + 48);
;             }
	v_mov_b32_e32 v94, v102
	v_mul_f32_e32 v90, v92, v84
	v_mul_f32_e32 v84, v91, v95
	v_pk_fma_f32 v[84:85], v[90:91], v[94:95], v[84:85] op_sel_hi:[1,1,0]
	v_mov_b32_e32 v92, v103
	v_mul_f32_e32 v88, v210, v88
	v_mov_b32_e32 v89, v84
	v_pk_mul_f32 v[88:89], v[88:89], v[92:93]
	s_waitcnt lgkmcnt(1)
	v_mov_b32_e32 v205, v97
	v_add_f32_e32 v90, v88, v89
	v_fma_f32 v88, -v204, v204, 1.0 clamp
	s_nop 0
	v_sqrt_f32_e32 v89, v88
	v_mov_b32_e32 v88, v96
	v_mul_f32_e32 v85, v95, v82
	v_mul_f32_e32 v94, v93, v85
	v_pk_mul_f32 v[88:89], v[86:87], v[88:89]
	s_waitcnt lgkmcnt(0)
	v_mov_b32_e32 v206, v208
	v_mul_f32_e32 v86, v97, v89
	v_pk_fma_f32 v[86:87], v[204:205], v[88:89], v[86:87] op_sel_hi:[1,1,0]
	v_fma_f32 v89, -v207, v207, 1.0 clamp
	s_nop 0
	v_sqrt_f32_e32 v89, v89
	v_mov_b32_e32 v93, v86
	v_mul_f32_e32 v96, v86, v207
	v_mul_f32_e32 v202, v196, v110
	v_mul_f32_e32 v92, v214, v89
	v_pk_fma_f32 v[92:93], v[92:93], v[206:207], v[96:97] op_sel_hi:[1,1,0]
	v_mul_f32_e32 v197, v197, v202
	v_fma_f32 v93, -v211, v211, 1.0 clamp
	s_nop 0
	v_sqrt_f32_e32 v93, v93
	v_mul_f32_e32 v196, v199, v201
	v_mov_b32_e32 v210, v209
	v_mov_b32_e32 v97, v92
	v_mul_f32_e32 v96, v215, v93
	v_fmac_f32_e32 v196, v200, v107
	v_mul_f32_e32 v107, v199, v197
	v_pk_mul_f32 v[96:97], v[96:97], v[210:211]
	v_mul_f32_e32 v100, v101, v98
	v_add_f32_e32 v93, v96, v97
	ds_bpermute_b32 v96, v124, v107
	ds_bpermute_b32 v97, v124, v196
	v_mul_f32_e32 v87, v204, v113
	v_mul_f32_e32 v89, v207, v87
	v_mul_f32_e32 v95, v211, v89
	s_waitcnt lgkmcnt(1)
	v_mul_f32_e32 v96, v107, v96
	s_waitcnt lgkmcnt(0)
	v_fma_f32 v97, v107, v97, v196
	v_cndmask_b32_e64 v96, v96, v107, s[4:5]
	v_cndmask_b32_e64 v97, v97, v196, s[4:5]
	ds_bpermute_b32 v101, v125, v96
	ds_bpermute_b32 v102, v125, v97
	s_waitcnt lgkmcnt(1)
	v_mul_f32_e32 v101, v96, v101
	s_waitcnt lgkmcnt(0)
	v_fma_f32 v102, v96, v102, v97
	v_cndmask_b32_e64 v96, v96, v101, s[6:7]
	v_cndmask_b32_e64 v97, v97, v102, s[6:7]
	ds_bpermute_b32 v101, v124, v96
	ds_bpermute_b32 v199, v164, v96
	ds_bpermute_b32 v96, v124, v100
	ds_bpermute_b32 v102, v124, v97
	ds_bpermute_b32 v200, v164, v97
	ds_bpermute_b32 v97, v124, v99
	s_waitcnt lgkmcnt(5)
	v_cndmask_b32_e64 v101, v101, 1.0, s[4:5]
	s_waitcnt lgkmcnt(3)
	v_mul_f32_e32 v96, v100, v96
	v_cndmask_b32_e64 v96, v96, v100, s[4:5]
	s_waitcnt lgkmcnt(2)
	v_cndmask_b32_e64 v198, v102, 0, s[4:5]
	s_waitcnt lgkmcnt(0)
	v_fma_f32 v97, v100, v97, v99
	v_cndmask_b32_e64 v97, v97, v99, s[4:5]
	ds_bpermute_b32 v102, v125, v96
	ds_bpermute_b32 v103, v125, v97
	v_fmac_f32_e32 v198, v146, v101
	v_fmac_f32_e32 v195, v110, v198
	v_fmac_f32_e32 v111, v202, v198
	s_waitcnt lgkmcnt(1)
	v_mul_f32_e32 v102, v96, v102
	s_waitcnt lgkmcnt(0)
	v_fma_f32 v103, v96, v103, v97
	v_cndmask_b32_e64 v96, v96, v102, s[6:7]
	v_cndmask_b32_e64 v97, v97, v103, s[6:7]
	ds_bpermute_b32 v102, v124, v96
	ds_bpermute_b32 v205, v164, v96
	ds_bpermute_b32 v96, v124, v94
	ds_bpermute_b32 v103, v124, v97
	ds_bpermute_b32 v206, v164, v97
	ds_bpermute_b32 v97, v124, v90
	s_waitcnt lgkmcnt(5)
	v_cndmask_b32_e64 v203, v102, 1.0, s[4:5]
	s_waitcnt lgkmcnt(3)
	v_mul_f32_e32 v96, v94, v96
	v_cndmask_b32_e64 v96, v96, v94, s[4:5]
	ds_bpermute_b32 v102, v125, v96
	s_waitcnt lgkmcnt(1)
	v_fma_f32 v97, v94, v97, v90
	v_cndmask_b32_e64 v97, v97, v90, s[4:5]
	v_cndmask_b32_e64 v204, v103, 0, s[4:5]
	ds_bpermute_b32 v103, v125, v97
	s_waitcnt lgkmcnt(1)
	v_mul_f32_e32 v102, v96, v102
	v_fmac_f32_e32 v201, v197, v198
	v_fmac_f32_e32 v196, v107, v198
	v_fmac_f32_e32 v200, v146, v199
	s_waitcnt lgkmcnt(0)
	v_fma_f32 v103, v96, v103, v97
	v_cndmask_b32_e64 v96, v96, v102, s[6:7]
	v_cndmask_b32_e64 v97, v97, v103, s[6:7]
	ds_bpermute_b32 v102, v124, v96
	ds_bpermute_b32 v209, v164, v96
	ds_bpermute_b32 v96, v124, v95
	ds_bpermute_b32 v103, v124, v97
	ds_bpermute_b32 v210, v164, v97
	ds_bpermute_b32 v97, v124, v93
	s_waitcnt lgkmcnt(5)
	v_cndmask_b32_e64 v207, v102, 1.0, s[4:5]
	s_waitcnt lgkmcnt(3)
	v_mul_f32_e32 v96, v95, v96
	v_cndmask_b32_e64 v96, v96, v95, s[4:5]
	ds_bpermute_b32 v102, v125, v96
	s_waitcnt lgkmcnt(1)
	v_fma_f32 v97, v95, v97, v93
	v_cndmask_b32_e64 v97, v97, v93, s[4:5]
	v_cndmask_b32_e64 v208, v103, 0, s[4:5]
	ds_bpermute_b32 v103, v125, v97
	s_waitcnt lgkmcnt(1)
	v_mul_f32_e32 v102, v96, v102
	v_fmac_f32_e32 v204, v200, v203
	v_fmac_f32_e32 v109, v108, v204
	v_fmac_f32_e32 v112, v106, v204
	s_waitcnt lgkmcnt(0)
; #define GAS __attribute__((address_space(1)))
; __device__ __forceinline__ unsigned pk2(float lo, float hi) { return pg8::cvt_pk_bf16(lo, hi); }
; __device__ __forceinline__ void lru_unit(Frame& F, int seq, int n) {
;     ...
;             const size_t r0 = rowbase + t0 + 4 * tq;
; #pragma unroll
;             for (int tt = 0; tt < 4; ++tt) {
;                 const float hin = EA[tt] * hc + EB[tt];
; #pragma unroll
;                 for (int rg = 0; rg < 4; ++rg) { const float h = A[tt][rg] * hin + B[tt][rg];
;                     const float y = h * bf2f(zc[4 * tt + rg]);
;                     *(GAS unsigned short*)(YAB + (r0 + 16 * tt + rg) * (2 * DM) + dg) = (unsigned short)(pk2(y, 0.f) & 0xffffu); }
;                 hc = TA[tt] * hc + TB[tt];
;             }
; #pragma unroll
;             for (int i = 0; i < 16; ++i) zc[i] = zn[i];
	v_fma_f32 v103, v96, v103, v97
	v_cndmask_b32_e64 v96, v96, v102, s[6:7]
	v_cndmask_b32_e64 v97, v97, v103, s[6:7]
	ds_bpermute_b32 v102, v124, v96
	ds_bpermute_b32 v103, v124, v97
	ds_bpermute_b32 v215, v164, v96
	s_nop 0
	v_mul_f32_e32 v96, v195, v176
	ds_bpermute_b32 v216, v164, v97
	v_cvt_pk_bf16_f32 v101, v96, v115
	v_lshl_add_u64 v[96:97], v[122:123], 0, s[0:1]
	s_waitcnt lgkmcnt(3)
	v_cndmask_b32_e64 v211, v102, 1.0, s[4:5]
	v_add_co_u32_e32 v102, vcc, s77, v96
	s_waitcnt lgkmcnt(2)
	v_cndmask_b32_e64 v214, v103, 0, s[4:5]
	v_addc_co_u32_e32 v103, vcc, 0, v97, vcc
	global_store_short v[102:103], v101, off offset:-4096
	s_nop 0
	v_mul_f32_e32 v101, v111, v173
	v_cvt_pk_bf16_f32 v101, v101, v115
	global_store_short v[102:103], v101, off
	s_waitcnt vmcnt(33)
	s_nop 0
	v_mul_f32_e32 v101, v201, v177
	v_add_co_u32_e32 v102, vcc, s78, v96
	v_cvt_pk_bf16_f32 v101, v101, v115
	v_fmac_f32_e32 v83, v98, v204
	s_nop 0
	v_addc_co_u32_e32 v103, vcc, 0, v97, vcc
	global_store_short v[102:103], v101, off offset:-4096
	s_waitcnt vmcnt(33)
	s_nop 0
	v_mul_f32_e32 v101, v196, v174
	v_cvt_pk_bf16_f32 v101, v101, v115
	global_store_short v[102:103], v101, off
	s_waitcnt vmcnt(32)
	s_nop 0
	v_mul_f32_e32 v101, v109, v178
	v_add_co_u32_e32 v102, vcc, s79, v96
	v_cvt_pk_bf16_f32 v101, v101, v115
	s_waitcnt vmcnt(31)
	s_nop 0
	v_addc_co_u32_e32 v103, vcc, 0, v97, vcc
	global_store_short v[102:103], v101, off offset:-4096
	s_nop 0
	v_mul_f32_e32 v101, v112, v167
	v_cvt_pk_bf16_f32 v101, v101, v115
	global_store_short v[102:103], v101, off
	v_mul_f32_e32 v83, v83, v175
	v_add_co_u32_e32 v102, vcc, s80, v96
	v_cvt_pk_bf16_f32 v83, v83, v115
	v_fmac_f32_e32 v99, v100, v204
	s_nop 0
	v_addc_co_u32_e32 v103, vcc, 0, v97, vcc
	global_store_short v[102:103], v83, off offset:-4096
	s_waitcnt vmcnt(33)
	s_nop 0
	v_mul_f32_e32 v83, v99, v172
	v_fmac_f32_e32 v206, v200, v205
	v_cvt_pk_bf16_f32 v83, v83, v115
	v_fmac_f32_e32 v208, v206, v207
	global_store_short v[102:103], v83, off
	v_fmac_f32_e32 v105, v104, v208
	s_waitcnt vmcnt(33)
	s_nop 0
	v_add_co_u32_e32 v98, vcc, s81, v96
	v_fmac_f32_e32 v91, v82, v208
	s_waitcnt vmcnt(32)
	s_nop 0
	v_mul_f32_e32 v83, v105, v168
	v_addc_co_u32_e32 v99, vcc, 0, v97, vcc
	v_mul_f32_e32 v82, v91, v166
	v_cvt_pk_bf16_f32 v83, v83, v115
	global_store_short v[98:99], v83, off offset:-4096
	v_cvt_pk_bf16_f32 v82, v82, v115
	global_store_short v[98:99], v82, off
	v_fmac_f32_e32 v84, v85, v208
	s_waitcnt vmcnt(33)
	s_nop 0
	v_mul_f32_e32 v82, v84, v165
	v_cvt_pk_bf16_f32 v84, v82, v115
	v_add_co_u32_e32 v82, vcc, s82, v96
	v_fmac_f32_e32 v90, v94, v208
	s_nop 0
	v_addc_co_u32_e32 v83, vcc, 0, v97, vcc
	global_store_short v[82:83], v84, off offset:-4096
	s_waitcnt vmcnt(33)
	s_nop 0
	v_fmac_f32_e32 v210, v206, v209
	v_mul_f32_e32 v84, v90, v161
	v_fmac_f32_e32 v214, v210, v211
	v_cvt_pk_bf16_f32 v84, v84, v115
	global_store_short v[82:83], v84, off
	v_fmac_f32_e32 v88, v113, v214
	s_waitcnt vmcnt(32)
	s_nop 0
	v_mul_f32_e32 v82, v88, v159
	v_cvt_pk_bf16_f32 v84, v82, v115
	v_add_co_u32_e32 v82, vcc, s83, v96
	v_fmac_f32_e32 v86, v87, v214
	s_nop 0
	v_addc_co_u32_e32 v83, vcc, 0, v97, vcc
	global_store_short v[82:83], v84, off offset:-4096
	s_nop 0
	v_mul_f32_e32 v84, v86, v154
	v_cvt_pk_bf16_f32 v84, v84, v115
	global_store_short v[82:83], v84, off
	v_fmac_f32_e32 v92, v89, v214
	s_waitcnt vmcnt(33)
	s_nop 0
	v_mul_f32_e32 v82, v92, v152
	v_cvt_pk_bf16_f32 v84, v82, v115
	v_add_co_u32_e32 v82, vcc, s84, v96
	v_fmac_f32_e32 v93, v95, v214
	s_nop 0
	v_addc_co_u32_e32 v83, vcc, 0, v97, vcc
	global_store_short v[82:83], v84, off
	s_waitcnt vmcnt(33)
	s_nop 0
	v_mul_f32_e32 v82, v93, v150
	v_cvt_pk_bf16_f32 v84, v82, v115
	v_add_co_u32_e32 v82, vcc, 0x4c433000, v96
	s_waitcnt lgkmcnt(0)
	v_mov_b32_e32 v146, v216
	v_addc_co_u32_e32 v83, vcc, 0, v97, vcc
	s_add_u32 s0, s0, 0x40000
	v_fmac_f32_e32 v146, v210, v215
	s_addc_u32 s1, s1, 0
	s_and_b64 vcc, exec, s[44:45]
	global_store_short v[82:83], v84, off
	s_cbranch_vccnz .LBB0_442
	s_waitcnt vmcnt(31)
	v_mov_b32_e32 v176, v179
	s_waitcnt vmcnt(30)
	v_mov_b32_e32 v173, v180
	s_waitcnt vmcnt(29)
	v_mov_b32_e32 v177, v181
	s_waitcnt vmcnt(28)
	v_mov_b32_e32 v174, v182
	s_waitcnt vmcnt(27)
	v_mov_b32_e32 v178, v183
	s_waitcnt vmcnt(26)
	v_mov_b32_e32 v167, v184
	s_waitcnt vmcnt(25)
	v_mov_b32_e32 v175, v185
	s_waitcnt vmcnt(24)
	v_mov_b32_e32 v172, v186
	s_waitcnt vmcnt(23)
	v_mov_b32_e32 v168, v187
	s_waitcnt vmcnt(22)
	v_mov_b32_e32 v166, v188
	s_waitcnt vmcnt(21)
	v_mov_b32_e32 v165, v189
	s_waitcnt vmcnt(20)
	v_mov_b32_e32 v161, v190
	s_waitcnt vmcnt(19)
	v_mov_b32_e32 v159, v191
	s_waitcnt vmcnt(18)
	v_mov_b32_e32 v154, v192
	s_waitcnt vmcnt(17)
	v_mov_b32_e32 v152, v193
	s_waitcnt vmcnt(16)
	v_mov_b32_e32 v150, v194
	s_branch .LBB0_438
